# FFN-up K-loops: LDS-DMA addresses as SGPR base + 32-bit VGPR offset; 16 v_lshl_add_u64 per iteration removed
# baseline (speedup 1.0000x reference)
;     ...
;     const bool has_next = unit(ui + 1, npm, npn, nsl, nhf);
;     const char* nA = has_next ? (const char*)A + (size_t)npm * 2 * hstepA + (nsl < 0 ? 0 : (size_t)nsl * nts * kstep) + (nhf > 0 ? hstepA : 0) : cA;
;     const char* nB = has_next ? (const char*)Bt + (size_t)npn * 2 * hstepB + (nsl < 0 ? 0 : (size_t)nsl * nts * kstep) : cB;
;     nhA = has_next ? (nhf < 0 ? hstepA : 0) : chA;
;     const int cnt = csl < 0 ? nt : nts;
.LBB0_305:
	s_add_u32 s0, s50, 0x100
	s_addc_u32 s1, s51, 0
	s_ashr_i32 s39, s38, 31
	s_lshl_b64 s[2:3], s[38:39], 19
	s_add_u32 s2, s8, s2
	s_addc_u32 s3, s9, s3
	s_cmp_gt_i32 s69, 0
	s_cselect_b32 s4, 0x40000, 0
	s_add_u32 s46, s2, s4
	s_addc_u32 s47, s3, 0
	s_and_b64 s[2:3], s[44:45], exec
	s_cselect_b32 s73, s47, s19
	s_cselect_b32 s74, s46, s18
	s_ashr_i32 s41, s40, 31
	s_lshl_b64 s[2:3], s[40:41], 19
	s_add_u32 s42, s16, s2
	s_addc_u32 s43, s17, s3
	s_and_b64 s[2:3], s[44:45], exec
	s_cselect_b32 s75, s43, s51
	s_cselect_b32 s76, s42, s50
	s_lshr_b32 s2, s69, 13
	v_lshl_add_u64 v[42:43], s[18:19], 0, v[136:137]
	v_lshl_add_u64 v[142:143], s[18:19], 0, v[138:139]
	s_and_b32 s26, s2, 0x40000
	v_lshl_add_u64 v[42:43], v[42:43], 0, s[24:25]
	v_lshl_add_u64 v[142:143], v[142:143], 0, s[24:25]
	s_mov_b32 s77, -2
	v_add_u32_e32 v246, 0x80, v132
	v_add_u32_e32 v247, 0x80, v134
.LBB0_306:
	s_add_u32 s2, s18, s48
	s_addc_u32 s3, s19, s49
	s_add_u32 s39, s2, 0x100
	v_add_u32_e32 v149, s62, v147
	s_addc_u32 s41, s3, 0
	ds_read_b128 v[152:155], v149
	ds_read_b128 v[156:159], v149 offset:1024
	ds_read_b128 v[160:163], v149 offset:2048
	ds_read_b128 v[164:167], v149 offset:3072
	s_add_u32 s50, s0, s48
	s_addc_u32 s51, s1, s49
	s_cmpk_eq_i32 s48, 0x700
	s_cselect_b64 s[2:3], -1, 0
	s_and_b64 s[4:5], s[2:3], exec
	s_cselect_b32 s51, s75, s51
	s_cselect_b32 s50, s76, s50
	s_cselect_b32 s5, s73, s41
	s_cselect_b32 s4, s74, s39
	s_add_i32 s39, s13, 0xc000
	v_add_u32_e32 v150, 0, v146
	s_add_u32 s100, s18, s24
	s_addc_u32 s101, s19, s25
	s_add_u32 s100, s100, s48
	s_addc_u32 s101, s101, s49
	s_mov_b32 m0, s39
	s_add_i32 s41, s13, 0xe000
	ds_read_b128 v[168:171], v150
	ds_read_b128 v[172:175], v150 offset:1024
	ds_read_b128 v[180:183], v150 offset:2048
	ds_read_b128 v[184:187], v150 offset:3072
	ds_read_b128 v[188:191], v150 offset:4096
	ds_read_b128 v[192:195], v150 offset:5120
	ds_read_b128 v[196:199], v150 offset:6144
	ds_read_b128 v[200:203], v150 offset:7168
	global_load_lds_dwordx4 v136, s[100:101]
	s_mov_b32 m0, s41
	s_nop 0
	global_load_lds_dwordx4 v138, s[100:101]
	s_waitcnt lgkmcnt(8)
	s_barrier
	s_waitcnt lgkmcnt(0)
	s_setprio 1
	s_waitcnt lgkmcnt(0)
	v_mfma_f32_16x16x32_bf16 v[64:67], v[152:155], v[168:171], v[64:67]
	v_mfma_f32_16x16x32_bf16 v[60:63], v[160:163], v[168:171], v[60:63]
	v_mfma_f32_16x16x32_bf16 v[56:59], v[152:155], v[180:183], v[56:59]
	v_mfma_f32_16x16x32_bf16 v[52:55], v[160:163], v[180:183], v[52:55]
	v_mfma_f32_16x16x32_bf16 v[36:39], v[152:155], v[188:191], v[36:39]
	v_mfma_f32_16x16x32_bf16 v[32:35], v[160:163], v[188:191], v[32:35]
	v_mfma_f32_16x16x32_bf16 v[20:23], v[152:155], v[196:199], v[20:23]
	v_mfma_f32_16x16x32_bf16 v[8:11], v[160:163], v[196:199], v[8:11]
	v_mfma_f32_16x16x32_bf16 v[64:67], v[156:159], v[172:175], v[64:67]
	v_mfma_f32_16x16x32_bf16 v[60:63], v[164:167], v[172:175], v[60:63]
	v_mfma_f32_16x16x32_bf16 v[56:59], v[156:159], v[184:187], v[56:59]
	v_mfma_f32_16x16x32_bf16 v[52:55], v[164:167], v[184:187], v[52:55]
	v_mfma_f32_16x16x32_bf16 v[36:39], v[156:159], v[192:195], v[36:39]
	v_mfma_f32_16x16x32_bf16 v[32:35], v[164:167], v[192:195], v[32:35]
	v_mfma_f32_16x16x32_bf16 v[20:23], v[156:159], v[200:203], v[20:23]
	v_mfma_f32_16x16x32_bf16 v[8:11], v[164:167], v[200:203], v[8:11]
	s_setprio 0
	s_barrier
	s_add_i32 s66, s62, s59
	v_add_u32_e32 v151, s63, v147
	s_mov_b32 m0, s66
	s_add_i32 s67, s66, 0x2000
	ds_read_b128 v[204:207], v151
	ds_read_b128 v[208:211], v151 offset:1024
	ds_read_b128 v[212:215], v151 offset:2048
	ds_read_b128 v[216:219], v151 offset:3072
	global_load_lds_dwordx4 v132, s[50:51]
	s_mov_b32 m0, s67
	s_nop 0
	global_load_lds_dwordx4 v134, s[50:51]
	s_barrier
	s_waitcnt lgkmcnt(0)
	s_setprio 1
	s_waitcnt lgkmcnt(0)
	v_mfma_f32_16x16x32_bf16 v[48:51], v[204:207], v[168:171], v[48:51]
	v_mfma_f32_16x16x32_bf16 v[44:47], v[212:215], v[168:171], v[44:47]
	v_mfma_f32_16x16x32_bf16 v[28:31], v[204:207], v[180:183], v[28:31]
	v_mfma_f32_16x16x32_bf16 v[24:27], v[212:215], v[180:183], v[24:27]
	v_mfma_f32_16x16x32_bf16 v[16:19], v[204:207], v[188:191], v[16:19]
	v_mfma_f32_16x16x32_bf16 v[12:15], v[212:215], v[188:191], v[12:15]
	v_mfma_f32_16x16x32_bf16 v[4:7], v[204:207], v[196:199], v[4:7]
	v_mfma_f32_16x16x32_bf16 v[0:3], v[212:215], v[196:199], v[0:3]
	v_mfma_f32_16x16x32_bf16 v[48:51], v[208:211], v[172:175], v[48:51]
	v_mfma_f32_16x16x32_bf16 v[44:47], v[216:219], v[172:175], v[44:47]
	v_mfma_f32_16x16x32_bf16 v[28:31], v[208:211], v[184:187], v[28:31]
	v_mfma_f32_16x16x32_bf16 v[24:27], v[216:219], v[184:187], v[24:27]
	v_mfma_f32_16x16x32_bf16 v[16:19], v[208:211], v[192:195], v[16:19]
	v_mfma_f32_16x16x32_bf16 v[12:15], v[216:219], v[192:195], v[12:15]
	v_mfma_f32_16x16x32_bf16 v[4:7], v[208:211], v[200:203], v[4:7]
	v_mfma_f32_16x16x32_bf16 v[0:3], v[216:219], v[200:203], v[0:3]
	s_setprio 0
	s_mov_b32 m0, s13
	s_barrier
	ds_read_b128 v[168:171], v150 offset:16384
	ds_read_b128 v[172:175], v150 offset:17408
	ds_read_b128 v[180:183], v150 offset:18432
	ds_read_b128 v[184:187], v150 offset:19456
	ds_read_b128 v[188:191], v150 offset:20480
	ds_read_b128 v[192:195], v150 offset:21504
	ds_read_b128 v[196:199], v150 offset:22528
	ds_read_b128 v[200:203], v150 offset:23552
	global_load_lds_dwordx4 v132, s[4:5]
	s_mov_b32 m0, s15
	s_nop 0
	global_load_lds_dwordx4 v134, s[4:5]
	s_barrier
	s_waitcnt lgkmcnt(0)
	s_setprio 1
	s_waitcnt lgkmcnt(0)
	v_mfma_f32_16x16x32_bf16 v[128:131], v[152:155], v[168:171], v[128:131]
	v_mfma_f32_16x16x32_bf16 v[124:127], v[160:163], v[168:171], v[124:127]
	v_mfma_f32_16x16x32_bf16 v[120:123], v[152:155], v[180:183], v[120:123]
	v_mfma_f32_16x16x32_bf16 v[116:119], v[160:163], v[180:183], v[116:119]
	v_mfma_f32_16x16x32_bf16 v[112:115], v[152:155], v[188:191], v[112:115]
	v_mfma_f32_16x16x32_bf16 v[108:111], v[160:163], v[188:191], v[108:111]
	v_mfma_f32_16x16x32_bf16 v[104:107], v[152:155], v[196:199], v[104:107]
	v_mfma_f32_16x16x32_bf16 v[100:103], v[160:163], v[196:199], v[100:103]
	v_mfma_f32_16x16x32_bf16 v[128:131], v[156:159], v[172:175], v[128:131]
	v_mfma_f32_16x16x32_bf16 v[124:127], v[164:167], v[172:175], v[124:127]
	v_mfma_f32_16x16x32_bf16 v[120:123], v[156:159], v[184:187], v[120:123]
	v_mfma_f32_16x16x32_bf16 v[116:119], v[164:167], v[184:187], v[116:119]
	v_mfma_f32_16x16x32_bf16 v[112:115], v[156:159], v[192:195], v[112:115]
	v_mfma_f32_16x16x32_bf16 v[108:111], v[164:167], v[192:195], v[108:111]
	v_mfma_f32_16x16x32_bf16 v[104:107], v[156:159], v[200:203], v[104:107]
	v_mfma_f32_16x16x32_bf16 v[100:103], v[164:167], v[200:203], v[100:103]
	s_setprio 0
	s_barrier
	s_add_u32 s78, s50, 0x40000
	s_addc_u32 s79, s51, 0
	s_add_i32 s70, s63, s59
	s_mov_b32 m0, s70
	s_add_i32 s71, s70, 0x2000
	global_load_lds_dwordx4 v132, s[78:79]
	s_mov_b32 m0, s71
	s_nop 0
	global_load_lds_dwordx4 v134, s[78:79]
	s_waitcnt vmcnt(6)
	s_barrier
	s_setprio 1
	v_mfma_f32_16x16x32_bf16 v[96:99], v[204:207], v[168:171], v[96:99]
	v_mfma_f32_16x16x32_bf16 v[92:95], v[212:215], v[168:171], v[92:95]
	v_mfma_f32_16x16x32_bf16 v[88:91], v[204:207], v[180:183], v[88:91]
	v_mfma_f32_16x16x32_bf16 v[84:87], v[212:215], v[180:183], v[84:87]
	v_mfma_f32_16x16x32_bf16 v[80:83], v[204:207], v[188:191], v[80:83]
	v_mfma_f32_16x16x32_bf16 v[76:79], v[212:215], v[188:191], v[76:79]
	v_mfma_f32_16x16x32_bf16 v[72:75], v[204:207], v[196:199], v[72:75]
	v_mfma_f32_16x16x32_bf16 v[68:71], v[212:215], v[196:199], v[68:71]
	v_mfma_f32_16x16x32_bf16 v[96:99], v[208:211], v[172:175], v[96:99]
	v_mfma_f32_16x16x32_bf16 v[92:95], v[216:219], v[172:175], v[92:95]
	v_mfma_f32_16x16x32_bf16 v[88:91], v[208:211], v[184:187], v[88:91]
	v_mfma_f32_16x16x32_bf16 v[84:87], v[216:219], v[184:187], v[84:87]
	v_mfma_f32_16x16x32_bf16 v[80:83], v[208:211], v[192:195], v[80:83]
	v_mfma_f32_16x16x32_bf16 v[76:79], v[216:219], v[192:195], v[76:79]
	v_mfma_f32_16x16x32_bf16 v[72:75], v[208:211], v[200:203], v[72:75]
	v_mfma_f32_16x16x32_bf16 v[68:71], v[216:219], v[200:203], v[68:71]
	s_setprio 0
	s_add_i32 s78, 0, 0x18000
	v_add_u32_e32 v152, s78, v147
	s_barrier
	ds_read_b128 v[154:157], v152
	ds_read_b128 v[158:161], v152 offset:1024
	ds_read_b128 v[162:165], v152 offset:2048
	ds_read_b128 v[166:169], v152 offset:3072
	s_and_b64 s[2:3], s[44:45], s[2:3]
	s_and_b64 s[2:3], s[2:3], exec
	s_cselect_b32 s2, s26, s24
	s_cselect_b32 s3, 0, s25
	s_add_u32 s2, s4, s2
	s_addc_u32 s3, s5, s3
	s_mov_b32 m0, s23
	ds_read_b128 v[170:173], v150 offset:32768
	ds_read_b128 v[180:183], v150 offset:33792
	ds_read_b128 v[184:187], v150 offset:34816
	ds_read_b128 v[188:191], v150 offset:35840
	ds_read_b128 v[192:195], v150 offset:36864
	ds_read_b128 v[196:199], v150 offset:37888
	ds_read_b128 v[200:203], v150 offset:38912
	ds_read_b128 v[204:207], v150 offset:39936
	global_load_lds_dwordx4 v132, s[2:3]
	s_mov_b32 m0, s54
	s_nop 0
	global_load_lds_dwordx4 v134, s[2:3]
	s_waitcnt lgkmcnt(8)
	s_barrier
	s_waitcnt lgkmcnt(0)
	s_setprio 1
	s_waitcnt lgkmcnt(0)
	v_mfma_f32_16x16x32_bf16 v[64:67], v[154:157], v[170:173], v[64:67]
	v_mfma_f32_16x16x32_bf16 v[60:63], v[162:165], v[170:173], v[60:63]
	v_mfma_f32_16x16x32_bf16 v[56:59], v[154:157], v[184:187], v[56:59]
	v_mfma_f32_16x16x32_bf16 v[52:55], v[162:165], v[184:187], v[52:55]
	v_mfma_f32_16x16x32_bf16 v[36:39], v[154:157], v[192:195], v[36:39]
	v_mfma_f32_16x16x32_bf16 v[32:35], v[162:165], v[192:195], v[32:35]
	v_mfma_f32_16x16x32_bf16 v[20:23], v[154:157], v[200:203], v[20:23]
	v_mfma_f32_16x16x32_bf16 v[8:11], v[162:165], v[200:203], v[8:11]
	v_mfma_f32_16x16x32_bf16 v[64:67], v[158:161], v[180:183], v[64:67]
	v_mfma_f32_16x16x32_bf16 v[60:63], v[166:169], v[180:183], v[60:63]
	v_mfma_f32_16x16x32_bf16 v[56:59], v[158:161], v[188:191], v[56:59]
	v_mfma_f32_16x16x32_bf16 v[52:55], v[166:169], v[188:191], v[52:55]
	v_mfma_f32_16x16x32_bf16 v[36:39], v[158:161], v[196:199], v[36:39]
	v_mfma_f32_16x16x32_bf16 v[32:35], v[166:169], v[196:199], v[32:35]
	v_mfma_f32_16x16x32_bf16 v[20:23], v[158:161], v[204:207], v[20:23]
	v_mfma_f32_16x16x32_bf16 v[8:11], v[166:169], v[204:207], v[8:11]
	s_setprio 0
	s_barrier
	s_add_i32 s79, 0, 0x1c000
	s_add_i32 s2, s78, s59
	v_add_u32_e32 v153, s79, v147
	s_mov_b32 m0, s2
	s_add_i32 s3, s2, 0x2000
	ds_read_b128 v[208:211], v153
	ds_read_b128 v[212:215], v153 offset:1024
	ds_read_b128 v[216:219], v153 offset:2048
	ds_read_b128 v[220:223], v153 offset:3072
	global_load_lds_dwordx4 v246, s[50:51]
	s_mov_b32 m0, s3
	s_nop 0
	global_load_lds_dwordx4 v247, s[50:51]
	s_barrier
	s_waitcnt lgkmcnt(0)
	s_setprio 1
	s_waitcnt lgkmcnt(0)
	v_mfma_f32_16x16x32_bf16 v[48:51], v[208:211], v[170:173], v[48:51]
	v_mfma_f32_16x16x32_bf16 v[44:47], v[216:219], v[170:173], v[44:47]
	v_mfma_f32_16x16x32_bf16 v[28:31], v[208:211], v[184:187], v[28:31]
	v_mfma_f32_16x16x32_bf16 v[24:27], v[216:219], v[184:187], v[24:27]
	v_mfma_f32_16x16x32_bf16 v[16:19], v[208:211], v[192:195], v[16:19]
	v_mfma_f32_16x16x32_bf16 v[12:15], v[216:219], v[192:195], v[12:15]
	v_mfma_f32_16x16x32_bf16 v[4:7], v[208:211], v[200:203], v[4:7]
	v_mfma_f32_16x16x32_bf16 v[0:3], v[216:219], v[200:203], v[0:3]
	v_mfma_f32_16x16x32_bf16 v[48:51], v[212:215], v[180:183], v[48:51]
	v_mfma_f32_16x16x32_bf16 v[44:47], v[220:223], v[180:183], v[44:47]
	v_mfma_f32_16x16x32_bf16 v[28:31], v[212:215], v[188:191], v[28:31]
	v_mfma_f32_16x16x32_bf16 v[24:27], v[220:223], v[188:191], v[24:27]
	v_mfma_f32_16x16x32_bf16 v[16:19], v[212:215], v[196:199], v[16:19]
	v_mfma_f32_16x16x32_bf16 v[12:15], v[220:223], v[196:199], v[12:15]
	v_mfma_f32_16x16x32_bf16 v[4:7], v[212:215], v[204:207], v[4:7]
	v_mfma_f32_16x16x32_bf16 v[0:3], v[220:223], v[204:207], v[0:3]
	s_setprio 0
	s_mov_b32 m0, s57
	s_barrier
	ds_read_b128 v[170:173], v150 offset:49152
	ds_read_b128 v[180:183], v150 offset:50176
	ds_read_b128 v[184:187], v150 offset:51200
	ds_read_b128 v[188:191], v150 offset:52224
	ds_read_b128 v[192:195], v150 offset:53248
	ds_read_b128 v[196:199], v150 offset:54272
	ds_read_b128 v[200:203], v150 offset:55296
	ds_read_b128 v[204:207], v150 offset:56320
	global_load_lds_dwordx4 v246, s[4:5]
	s_mov_b32 m0, s58
	s_nop 0
	global_load_lds_dwordx4 v247, s[4:5]
	s_barrier
	s_waitcnt lgkmcnt(0)
	s_setprio 1
	s_waitcnt lgkmcnt(0)
	v_mfma_f32_16x16x32_bf16 v[128:131], v[154:157], v[170:173], v[128:131]
	v_mfma_f32_16x16x32_bf16 v[124:127], v[162:165], v[170:173], v[124:127]
	v_mfma_f32_16x16x32_bf16 v[120:123], v[154:157], v[184:187], v[120:123]
	v_mfma_f32_16x16x32_bf16 v[116:119], v[162:165], v[184:187], v[116:119]
	v_mfma_f32_16x16x32_bf16 v[112:115], v[154:157], v[192:195], v[112:115]
	v_mfma_f32_16x16x32_bf16 v[108:111], v[162:165], v[192:195], v[108:111]
	v_mfma_f32_16x16x32_bf16 v[104:107], v[154:157], v[200:203], v[104:107]
	v_mfma_f32_16x16x32_bf16 v[100:103], v[162:165], v[200:203], v[100:103]
	v_mfma_f32_16x16x32_bf16 v[128:131], v[158:161], v[180:183], v[128:131]
	v_mfma_f32_16x16x32_bf16 v[124:127], v[166:169], v[180:183], v[124:127]
	v_mfma_f32_16x16x32_bf16 v[120:123], v[158:161], v[188:191], v[120:123]
	v_mfma_f32_16x16x32_bf16 v[116:119], v[166:169], v[188:191], v[116:119]
	v_mfma_f32_16x16x32_bf16 v[112:115], v[158:161], v[196:199], v[112:115]
	v_mfma_f32_16x16x32_bf16 v[108:111], v[166:169], v[196:199], v[108:111]
	v_mfma_f32_16x16x32_bf16 v[104:107], v[158:161], v[204:207], v[104:107]
	v_mfma_f32_16x16x32_bf16 v[100:103], v[166:169], v[204:207], v[100:103]
	s_setprio 0
	s_barrier
	s_add_u32 s4, s50, 0x40080
	s_addc_u32 s5, s51, 0
	s_add_i32 s50, s79, s59
	s_mov_b32 m0, s50
	s_add_i32 s51, s50, 0x2000
	global_load_lds_dwordx4 v132, s[4:5]
	s_mov_b32 m0, s51
	s_nop 0
	global_load_lds_dwordx4 v134, s[4:5]
	s_waitcnt vmcnt(6)
	s_barrier
	s_setprio 1
	v_mfma_f32_16x16x32_bf16 v[96:99], v[208:211], v[170:173], v[96:99]
	v_mfma_f32_16x16x32_bf16 v[92:95], v[216:219], v[170:173], v[92:95]
	v_mfma_f32_16x16x32_bf16 v[88:91], v[208:211], v[184:187], v[88:91]
	v_mfma_f32_16x16x32_bf16 v[84:87], v[216:219], v[184:187], v[84:87]
	v_mfma_f32_16x16x32_bf16 v[80:83], v[208:211], v[192:195], v[80:83]
	v_mfma_f32_16x16x32_bf16 v[76:79], v[216:219], v[192:195], v[76:79]
	v_mfma_f32_16x16x32_bf16 v[72:75], v[208:211], v[200:203], v[72:75]
	v_mfma_f32_16x16x32_bf16 v[68:71], v[216:219], v[200:203], v[68:71]
	v_mfma_f32_16x16x32_bf16 v[96:99], v[212:215], v[180:183], v[96:99]
	v_mfma_f32_16x16x32_bf16 v[92:95], v[220:223], v[180:183], v[92:95]
	v_mfma_f32_16x16x32_bf16 v[88:91], v[212:215], v[188:191], v[88:91]
	v_mfma_f32_16x16x32_bf16 v[84:87], v[220:223], v[188:191], v[84:87]
	v_mfma_f32_16x16x32_bf16 v[80:83], v[212:215], v[196:199], v[80:83]
	v_mfma_f32_16x16x32_bf16 v[76:79], v[220:223], v[196:199], v[76:79]
	v_mfma_f32_16x16x32_bf16 v[72:75], v[212:215], v[204:207], v[72:75]
	v_mfma_f32_16x16x32_bf16 v[68:71], v[220:223], v[204:207], v[68:71]
	s_setprio 0
	s_add_i32 s77, s77, 2
	s_add_u32 s48, s48, 0x100
	s_addc_u32 s49, s49, 0
	s_cmp_gt_u32 s77, 13
	s_barrier
	s_cbranch_scc0 .LBB0_306
	s_cmp_lt_i32 s22, 0
	s_cbranch_scc1 .LBB0_309
	s_add_u32 s0, s0, 0xffffff00
	s_addc_u32 s1, s1, -1
	s_andn2_b64 vcc, exec, s[44:45]
	s_cbranch_vccnz .LBB0_295
	s_branch .LBB0_310

;     ...
;     const bool has_next = unit(ui + 1, npm, npn, nsl, nhf);
;     const char* nA = has_next ? (const char*)A + (size_t)npm * 2 * hstepA + (nsl < 0 ? 0 : (size_t)nsl * nts * kstep) + (nhf > 0 ? hstepA : 0) : cA;
;     const char* nB = has_next ? (const char*)Bt + (size_t)npn * 2 * hstepB + (nsl < 0 ? 0 : (size_t)nsl * nts * kstep) : cB;
;     nhA = has_next ? (nhf < 0 ? hstepA : 0) : chA;
;     const int cnt = csl < 0 ? nt : nts;
.LBB0_1605:
	s_add_u32 s0, s50, 0x100
	s_addc_u32 s1, s51, 0
	s_ashr_i32 s39, s38, 31
	s_lshl_b64 s[2:3], s[38:39], 19
	s_add_u32 s2, s8, s2
	s_addc_u32 s3, s9, s3
	s_cmp_gt_i32 s69, 0
	s_cselect_b32 s4, 0x40000, 0
	s_add_u32 s46, s2, s4
	s_addc_u32 s47, s3, 0
	s_and_b64 s[2:3], s[44:45], exec
	s_cselect_b32 s73, s47, s19
	s_cselect_b32 s74, s46, s18
	s_ashr_i32 s41, s40, 31
	s_lshl_b64 s[2:3], s[40:41], 19
	s_add_u32 s42, s16, s2
	s_addc_u32 s43, s17, s3
	s_and_b64 s[2:3], s[44:45], exec
	s_cselect_b32 s75, s43, s51
	s_cselect_b32 s76, s42, s50
	s_lshr_b32 s2, s69, 13
	v_lshl_add_u64 v[50:51], s[18:19], 0, v[136:137]
	v_lshl_add_u64 v[142:143], s[18:19], 0, v[138:139]
	s_and_b32 s26, s2, 0x40000
	v_lshl_add_u64 v[50:51], v[50:51], 0, s[24:25]
	v_lshl_add_u64 v[142:143], v[142:143], 0, s[24:25]
	s_mov_b32 s77, -2
	v_add_u32_e32 v246, 0x80, v132
	v_add_u32_e32 v247, 0x80, v134
.LBB0_1606:
	s_add_u32 s2, s18, s48
	s_addc_u32 s3, s19, s49
	s_add_u32 s39, s2, 0x100
	v_add_u32_e32 v149, s62, v147
	s_addc_u32 s41, s3, 0
	ds_read_b128 v[152:155], v149
	ds_read_b128 v[156:159], v149 offset:1024
	ds_read_b128 v[160:163], v149 offset:2048
	ds_read_b128 v[164:167], v149 offset:3072
	s_add_u32 s50, s0, s48
	s_addc_u32 s51, s1, s49
	s_cmpk_eq_i32 s48, 0x700
	s_cselect_b64 s[2:3], -1, 0
	s_and_b64 s[4:5], s[2:3], exec
	s_cselect_b32 s51, s75, s51
	s_cselect_b32 s50, s76, s50
	s_cselect_b32 s5, s73, s41
	s_cselect_b32 s4, s74, s39
	s_add_i32 s39, s13, 0xc000
	v_add_u32_e32 v150, 0, v146
	s_add_u32 s100, s18, s24
	s_addc_u32 s101, s19, s25
	s_add_u32 s100, s100, s48
	s_addc_u32 s101, s101, s49
	s_mov_b32 m0, s39
	s_add_i32 s41, s13, 0xe000
	ds_read_b128 v[168:171], v150
	ds_read_b128 v[172:175], v150 offset:1024
	ds_read_b128 v[180:183], v150 offset:2048
	ds_read_b128 v[184:187], v150 offset:3072
	ds_read_b128 v[188:191], v150 offset:4096
	ds_read_b128 v[192:195], v150 offset:5120
	ds_read_b128 v[196:199], v150 offset:6144
	ds_read_b128 v[200:203], v150 offset:7168
	global_load_lds_dwordx4 v136, s[100:101]
	s_mov_b32 m0, s41
	s_nop 0
	global_load_lds_dwordx4 v138, s[100:101]
	s_waitcnt lgkmcnt(8)
	s_barrier
	s_waitcnt lgkmcnt(0)
	s_setprio 1
	s_waitcnt lgkmcnt(0)
	v_mfma_f32_16x16x32_bf16 v[64:67], v[152:155], v[168:171], v[64:67]
	v_mfma_f32_16x16x32_bf16 v[60:63], v[160:163], v[168:171], v[60:63]
	v_mfma_f32_16x16x32_bf16 v[44:47], v[152:155], v[180:183], v[44:47]
	v_mfma_f32_16x16x32_bf16 v[40:43], v[160:163], v[180:183], v[40:43]
	v_mfma_f32_16x16x32_bf16 v[28:31], v[152:155], v[188:191], v[28:31]
	v_mfma_f32_16x16x32_bf16 v[24:27], v[160:163], v[188:191], v[24:27]
	v_mfma_f32_16x16x32_bf16 v[12:15], v[152:155], v[196:199], v[12:15]
	v_mfma_f32_16x16x32_bf16 v[8:11], v[160:163], v[196:199], v[8:11]
	v_mfma_f32_16x16x32_bf16 v[64:67], v[156:159], v[172:175], v[64:67]
	v_mfma_f32_16x16x32_bf16 v[60:63], v[164:167], v[172:175], v[60:63]
	v_mfma_f32_16x16x32_bf16 v[44:47], v[156:159], v[184:187], v[44:47]
	v_mfma_f32_16x16x32_bf16 v[40:43], v[164:167], v[184:187], v[40:43]
	v_mfma_f32_16x16x32_bf16 v[28:31], v[156:159], v[192:195], v[28:31]
	v_mfma_f32_16x16x32_bf16 v[24:27], v[164:167], v[192:195], v[24:27]
	v_mfma_f32_16x16x32_bf16 v[12:15], v[156:159], v[200:203], v[12:15]
	v_mfma_f32_16x16x32_bf16 v[8:11], v[164:167], v[200:203], v[8:11]
	s_setprio 0
	s_barrier
	s_add_i32 s66, s62, s59
	v_add_u32_e32 v151, s63, v147
	s_mov_b32 m0, s66
	s_add_i32 s67, s66, 0x2000
	ds_read_b128 v[204:207], v151
	ds_read_b128 v[208:211], v151 offset:1024
	ds_read_b128 v[212:215], v151 offset:2048
	ds_read_b128 v[216:219], v151 offset:3072
	global_load_lds_dwordx4 v132, s[50:51]
	s_mov_b32 m0, s67
	s_nop 0
	global_load_lds_dwordx4 v134, s[50:51]
	s_barrier
	s_waitcnt lgkmcnt(0)
	s_setprio 1
	s_waitcnt lgkmcnt(0)
	v_mfma_f32_16x16x32_bf16 v[56:59], v[204:207], v[168:171], v[56:59]
	v_mfma_f32_16x16x32_bf16 v[52:55], v[212:215], v[168:171], v[52:55]
	v_mfma_f32_16x16x32_bf16 v[36:39], v[204:207], v[180:183], v[36:39]
	v_mfma_f32_16x16x32_bf16 v[32:35], v[212:215], v[180:183], v[32:35]
	v_mfma_f32_16x16x32_bf16 v[20:23], v[204:207], v[188:191], v[20:23]
	v_mfma_f32_16x16x32_bf16 v[16:19], v[212:215], v[188:191], v[16:19]
	v_mfma_f32_16x16x32_bf16 v[4:7], v[204:207], v[196:199], v[4:7]
	v_mfma_f32_16x16x32_bf16 v[0:3], v[212:215], v[196:199], v[0:3]
	v_mfma_f32_16x16x32_bf16 v[56:59], v[208:211], v[172:175], v[56:59]
	v_mfma_f32_16x16x32_bf16 v[52:55], v[216:219], v[172:175], v[52:55]
	v_mfma_f32_16x16x32_bf16 v[36:39], v[208:211], v[184:187], v[36:39]
	v_mfma_f32_16x16x32_bf16 v[32:35], v[216:219], v[184:187], v[32:35]
	v_mfma_f32_16x16x32_bf16 v[20:23], v[208:211], v[192:195], v[20:23]
	v_mfma_f32_16x16x32_bf16 v[16:19], v[216:219], v[192:195], v[16:19]
	v_mfma_f32_16x16x32_bf16 v[4:7], v[208:211], v[200:203], v[4:7]
	v_mfma_f32_16x16x32_bf16 v[0:3], v[216:219], v[200:203], v[0:3]
	s_setprio 0
	s_mov_b32 m0, s13
	s_barrier
	ds_read_b128 v[168:171], v150 offset:16384
	ds_read_b128 v[172:175], v150 offset:17408
	ds_read_b128 v[180:183], v150 offset:18432
	ds_read_b128 v[184:187], v150 offset:19456
	ds_read_b128 v[188:191], v150 offset:20480
	ds_read_b128 v[192:195], v150 offset:21504
	ds_read_b128 v[196:199], v150 offset:22528
	ds_read_b128 v[200:203], v150 offset:23552
	global_load_lds_dwordx4 v132, s[4:5]
	s_mov_b32 m0, s15
	s_nop 0
	global_load_lds_dwordx4 v134, s[4:5]
	s_barrier
	s_waitcnt lgkmcnt(0)
	s_setprio 1
	s_waitcnt lgkmcnt(0)
	v_mfma_f32_16x16x32_bf16 v[128:131], v[152:155], v[168:171], v[128:131]
	v_mfma_f32_16x16x32_bf16 v[124:127], v[160:163], v[168:171], v[124:127]
	v_mfma_f32_16x16x32_bf16 v[120:123], v[152:155], v[180:183], v[120:123]
	v_mfma_f32_16x16x32_bf16 v[116:119], v[160:163], v[180:183], v[116:119]
	v_mfma_f32_16x16x32_bf16 v[112:115], v[152:155], v[188:191], v[112:115]
	v_mfma_f32_16x16x32_bf16 v[108:111], v[160:163], v[188:191], v[108:111]
	v_mfma_f32_16x16x32_bf16 v[104:107], v[152:155], v[196:199], v[104:107]
	v_mfma_f32_16x16x32_bf16 v[100:103], v[160:163], v[196:199], v[100:103]
	v_mfma_f32_16x16x32_bf16 v[128:131], v[156:159], v[172:175], v[128:131]
	v_mfma_f32_16x16x32_bf16 v[124:127], v[164:167], v[172:175], v[124:127]
	v_mfma_f32_16x16x32_bf16 v[120:123], v[156:159], v[184:187], v[120:123]
	v_mfma_f32_16x16x32_bf16 v[116:119], v[164:167], v[184:187], v[116:119]
	v_mfma_f32_16x16x32_bf16 v[112:115], v[156:159], v[192:195], v[112:115]
	v_mfma_f32_16x16x32_bf16 v[108:111], v[164:167], v[192:195], v[108:111]
	v_mfma_f32_16x16x32_bf16 v[104:107], v[156:159], v[200:203], v[104:107]
	v_mfma_f32_16x16x32_bf16 v[100:103], v[164:167], v[200:203], v[100:103]
	s_setprio 0
	s_barrier
	s_add_u32 s78, s50, 0x40000
	s_addc_u32 s79, s51, 0
	s_add_i32 s70, s63, s59
	s_mov_b32 m0, s70
	s_add_i32 s71, s70, 0x2000
	global_load_lds_dwordx4 v132, s[78:79]
	s_mov_b32 m0, s71
	s_nop 0
	global_load_lds_dwordx4 v134, s[78:79]
	s_waitcnt vmcnt(6)
	s_barrier
	s_setprio 1
	v_mfma_f32_16x16x32_bf16 v[96:99], v[204:207], v[168:171], v[96:99]
	v_mfma_f32_16x16x32_bf16 v[92:95], v[212:215], v[168:171], v[92:95]
	v_mfma_f32_16x16x32_bf16 v[88:91], v[204:207], v[180:183], v[88:91]
	v_mfma_f32_16x16x32_bf16 v[84:87], v[212:215], v[180:183], v[84:87]
	v_mfma_f32_16x16x32_bf16 v[80:83], v[204:207], v[188:191], v[80:83]
	v_mfma_f32_16x16x32_bf16 v[76:79], v[212:215], v[188:191], v[76:79]
	v_mfma_f32_16x16x32_bf16 v[72:75], v[204:207], v[196:199], v[72:75]
	v_mfma_f32_16x16x32_bf16 v[68:71], v[212:215], v[196:199], v[68:71]
	v_mfma_f32_16x16x32_bf16 v[96:99], v[208:211], v[172:175], v[96:99]
	v_mfma_f32_16x16x32_bf16 v[92:95], v[216:219], v[172:175], v[92:95]
	v_mfma_f32_16x16x32_bf16 v[88:91], v[208:211], v[184:187], v[88:91]
	v_mfma_f32_16x16x32_bf16 v[84:87], v[216:219], v[184:187], v[84:87]
	v_mfma_f32_16x16x32_bf16 v[80:83], v[208:211], v[192:195], v[80:83]
	v_mfma_f32_16x16x32_bf16 v[76:79], v[216:219], v[192:195], v[76:79]
	v_mfma_f32_16x16x32_bf16 v[72:75], v[208:211], v[200:203], v[72:75]
	v_mfma_f32_16x16x32_bf16 v[68:71], v[216:219], v[200:203], v[68:71]
	s_setprio 0
	s_add_i32 s78, 0, 0x18000
	v_add_u32_e32 v152, s78, v147
	s_barrier
	ds_read_b128 v[154:157], v152
	ds_read_b128 v[158:161], v152 offset:1024
	ds_read_b128 v[162:165], v152 offset:2048
	ds_read_b128 v[166:169], v152 offset:3072
	s_and_b64 s[2:3], s[44:45], s[2:3]
	s_and_b64 s[2:3], s[2:3], exec
	s_cselect_b32 s2, s26, s24
	s_cselect_b32 s3, 0, s25
	s_add_u32 s2, s4, s2
	s_addc_u32 s3, s5, s3
	s_mov_b32 m0, s23
	ds_read_b128 v[170:173], v150 offset:32768
	ds_read_b128 v[180:183], v150 offset:33792
	ds_read_b128 v[184:187], v150 offset:34816
	ds_read_b128 v[188:191], v150 offset:35840
	ds_read_b128 v[192:195], v150 offset:36864
	ds_read_b128 v[196:199], v150 offset:37888
	ds_read_b128 v[200:203], v150 offset:38912
	ds_read_b128 v[204:207], v150 offset:39936
	global_load_lds_dwordx4 v132, s[2:3]
	s_mov_b32 m0, s54
	s_nop 0
	global_load_lds_dwordx4 v134, s[2:3]
	s_waitcnt lgkmcnt(8)
	s_barrier
	s_waitcnt lgkmcnt(0)
	s_setprio 1
	s_waitcnt lgkmcnt(0)
	v_mfma_f32_16x16x32_bf16 v[64:67], v[154:157], v[170:173], v[64:67]
	v_mfma_f32_16x16x32_bf16 v[60:63], v[162:165], v[170:173], v[60:63]
	v_mfma_f32_16x16x32_bf16 v[44:47], v[154:157], v[184:187], v[44:47]
	v_mfma_f32_16x16x32_bf16 v[40:43], v[162:165], v[184:187], v[40:43]
	v_mfma_f32_16x16x32_bf16 v[28:31], v[154:157], v[192:195], v[28:31]
	v_mfma_f32_16x16x32_bf16 v[24:27], v[162:165], v[192:195], v[24:27]
	v_mfma_f32_16x16x32_bf16 v[12:15], v[154:157], v[200:203], v[12:15]
	v_mfma_f32_16x16x32_bf16 v[8:11], v[162:165], v[200:203], v[8:11]
	v_mfma_f32_16x16x32_bf16 v[64:67], v[158:161], v[180:183], v[64:67]
	v_mfma_f32_16x16x32_bf16 v[60:63], v[166:169], v[180:183], v[60:63]
	v_mfma_f32_16x16x32_bf16 v[44:47], v[158:161], v[188:191], v[44:47]
	v_mfma_f32_16x16x32_bf16 v[40:43], v[166:169], v[188:191], v[40:43]
	v_mfma_f32_16x16x32_bf16 v[28:31], v[158:161], v[196:199], v[28:31]
	v_mfma_f32_16x16x32_bf16 v[24:27], v[166:169], v[196:199], v[24:27]
	v_mfma_f32_16x16x32_bf16 v[12:15], v[158:161], v[204:207], v[12:15]
	v_mfma_f32_16x16x32_bf16 v[8:11], v[166:169], v[204:207], v[8:11]
	s_setprio 0
	s_barrier
	s_add_i32 s79, 0, 0x1c000
	s_add_i32 s2, s78, s59
	v_add_u32_e32 v153, s79, v147
	s_mov_b32 m0, s2
	s_add_i32 s3, s2, 0x2000
	ds_read_b128 v[208:211], v153
	ds_read_b128 v[212:215], v153 offset:1024
	ds_read_b128 v[216:219], v153 offset:2048
	ds_read_b128 v[220:223], v153 offset:3072
	global_load_lds_dwordx4 v246, s[50:51]
	s_mov_b32 m0, s3
	s_nop 0
	global_load_lds_dwordx4 v247, s[50:51]
	s_barrier
	s_waitcnt lgkmcnt(0)
	s_setprio 1
	s_waitcnt lgkmcnt(0)
	v_mfma_f32_16x16x32_bf16 v[56:59], v[208:211], v[170:173], v[56:59]
	v_mfma_f32_16x16x32_bf16 v[52:55], v[216:219], v[170:173], v[52:55]
	v_mfma_f32_16x16x32_bf16 v[36:39], v[208:211], v[184:187], v[36:39]
	v_mfma_f32_16x16x32_bf16 v[32:35], v[216:219], v[184:187], v[32:35]
	v_mfma_f32_16x16x32_bf16 v[20:23], v[208:211], v[192:195], v[20:23]
	v_mfma_f32_16x16x32_bf16 v[16:19], v[216:219], v[192:195], v[16:19]
	v_mfma_f32_16x16x32_bf16 v[4:7], v[208:211], v[200:203], v[4:7]
	v_mfma_f32_16x16x32_bf16 v[0:3], v[216:219], v[200:203], v[0:3]
	v_mfma_f32_16x16x32_bf16 v[56:59], v[212:215], v[180:183], v[56:59]
	v_mfma_f32_16x16x32_bf16 v[52:55], v[220:223], v[180:183], v[52:55]
	v_mfma_f32_16x16x32_bf16 v[36:39], v[212:215], v[188:191], v[36:39]
	v_mfma_f32_16x16x32_bf16 v[32:35], v[220:223], v[188:191], v[32:35]
	v_mfma_f32_16x16x32_bf16 v[20:23], v[212:215], v[196:199], v[20:23]
	v_mfma_f32_16x16x32_bf16 v[16:19], v[220:223], v[196:199], v[16:19]
	v_mfma_f32_16x16x32_bf16 v[4:7], v[212:215], v[204:207], v[4:7]
	v_mfma_f32_16x16x32_bf16 v[0:3], v[220:223], v[204:207], v[0:3]
	s_setprio 0
	s_mov_b32 m0, s57
	s_barrier
	ds_read_b128 v[170:173], v150 offset:49152
	ds_read_b128 v[180:183], v150 offset:50176
	ds_read_b128 v[184:187], v150 offset:51200
	ds_read_b128 v[188:191], v150 offset:52224
	ds_read_b128 v[192:195], v150 offset:53248
	ds_read_b128 v[196:199], v150 offset:54272
	ds_read_b128 v[200:203], v150 offset:55296
	ds_read_b128 v[204:207], v150 offset:56320
	global_load_lds_dwordx4 v246, s[4:5]
	s_mov_b32 m0, s58
	s_nop 0
	global_load_lds_dwordx4 v247, s[4:5]
	s_barrier
	s_waitcnt lgkmcnt(0)
	s_setprio 1
	s_waitcnt lgkmcnt(0)
	v_mfma_f32_16x16x32_bf16 v[128:131], v[154:157], v[170:173], v[128:131]
	v_mfma_f32_16x16x32_bf16 v[124:127], v[162:165], v[170:173], v[124:127]
	v_mfma_f32_16x16x32_bf16 v[120:123], v[154:157], v[184:187], v[120:123]
	v_mfma_f32_16x16x32_bf16 v[116:119], v[162:165], v[184:187], v[116:119]
	v_mfma_f32_16x16x32_bf16 v[112:115], v[154:157], v[192:195], v[112:115]
	v_mfma_f32_16x16x32_bf16 v[108:111], v[162:165], v[192:195], v[108:111]
	v_mfma_f32_16x16x32_bf16 v[104:107], v[154:157], v[200:203], v[104:107]
	v_mfma_f32_16x16x32_bf16 v[100:103], v[162:165], v[200:203], v[100:103]
	v_mfma_f32_16x16x32_bf16 v[128:131], v[158:161], v[180:183], v[128:131]
	v_mfma_f32_16x16x32_bf16 v[124:127], v[166:169], v[180:183], v[124:127]
	v_mfma_f32_16x16x32_bf16 v[120:123], v[158:161], v[188:191], v[120:123]
	v_mfma_f32_16x16x32_bf16 v[116:119], v[166:169], v[188:191], v[116:119]
	v_mfma_f32_16x16x32_bf16 v[112:115], v[158:161], v[196:199], v[112:115]
	v_mfma_f32_16x16x32_bf16 v[108:111], v[166:169], v[196:199], v[108:111]
	v_mfma_f32_16x16x32_bf16 v[104:107], v[158:161], v[204:207], v[104:107]
	v_mfma_f32_16x16x32_bf16 v[100:103], v[166:169], v[204:207], v[100:103]
	s_setprio 0
	s_barrier
	s_add_u32 s4, s50, 0x40080
	s_addc_u32 s5, s51, 0
	s_add_i32 s50, s79, s59
	s_mov_b32 m0, s50
	s_add_i32 s51, s50, 0x2000
	global_load_lds_dwordx4 v132, s[4:5]
	s_mov_b32 m0, s51
	s_nop 0
	global_load_lds_dwordx4 v134, s[4:5]
	s_waitcnt vmcnt(6)
	s_barrier
	s_setprio 1
	v_mfma_f32_16x16x32_bf16 v[96:99], v[208:211], v[170:173], v[96:99]
	v_mfma_f32_16x16x32_bf16 v[92:95], v[216:219], v[170:173], v[92:95]
	v_mfma_f32_16x16x32_bf16 v[88:91], v[208:211], v[184:187], v[88:91]
	v_mfma_f32_16x16x32_bf16 v[84:87], v[216:219], v[184:187], v[84:87]
	v_mfma_f32_16x16x32_bf16 v[80:83], v[208:211], v[192:195], v[80:83]
	v_mfma_f32_16x16x32_bf16 v[76:79], v[216:219], v[192:195], v[76:79]
	v_mfma_f32_16x16x32_bf16 v[72:75], v[208:211], v[200:203], v[72:75]
	v_mfma_f32_16x16x32_bf16 v[68:71], v[216:219], v[200:203], v[68:71]
	v_mfma_f32_16x16x32_bf16 v[96:99], v[212:215], v[180:183], v[96:99]
	v_mfma_f32_16x16x32_bf16 v[92:95], v[220:223], v[180:183], v[92:95]
	v_mfma_f32_16x16x32_bf16 v[88:91], v[212:215], v[188:191], v[88:91]
	v_mfma_f32_16x16x32_bf16 v[84:87], v[220:223], v[188:191], v[84:87]
	v_mfma_f32_16x16x32_bf16 v[80:83], v[212:215], v[196:199], v[80:83]
	v_mfma_f32_16x16x32_bf16 v[76:79], v[220:223], v[196:199], v[76:79]
	v_mfma_f32_16x16x32_bf16 v[72:75], v[212:215], v[204:207], v[72:75]
	v_mfma_f32_16x16x32_bf16 v[68:71], v[220:223], v[204:207], v[68:71]
	s_setprio 0
	s_add_i32 s77, s77, 2
	s_add_u32 s48, s48, 0x100
	s_addc_u32 s49, s49, 0
	s_cmp_gt_u32 s77, 13
	s_barrier
	s_cbranch_scc0 .LBB0_1606
	s_cmp_lt_i32 s22, 0
	s_cbranch_scc1 .LBB0_1609
	s_add_u32 s0, s0, 0xffffff00
	s_addc_u32 s1, s1, -1
	s_andn2_b64 vcc, exec, s[44:45]
	s_cbranch_vccnz .LBB0_1595
	s_branch .LBB0_1610

;     ...
;     const bool has_next = unit(ui + 1, npm, npn, nsl, nhf);
;     const char* nA = has_next ? (const char*)A + (size_t)npm * 2 * hstepA + (nsl < 0 ? 0 : (size_t)nsl * nts * kstep) + (nhf > 0 ? hstepA : 0) : cA;
;     const char* nB = has_next ? (const char*)Bt + (size_t)npn * 2 * hstepB + (nsl < 0 ? 0 : (size_t)nsl * nts * kstep) : cB;
;     nhA = has_next ? (nhf < 0 ? hstepA : 0) : chA;
;     const int cnt = csl < 0 ? nt : nts;
.LBB0_2594:
	s_add_u32 s0, s50, 0x100
	s_addc_u32 s1, s51, 0
	s_ashr_i32 s41, s40, 31
	s_lshl_b64 s[2:3], s[40:41], 19
	s_add_u32 s2, s8, s2
	s_addc_u32 s3, s9, s3
	s_cmp_gt_i32 s69, 0
	s_cselect_b32 s4, 0x40000, 0
	s_add_u32 s46, s2, s4
	s_addc_u32 s47, s3, 0
	s_and_b64 s[2:3], s[44:45], exec
	s_cselect_b32 s73, s47, s19
	s_cselect_b32 s74, s46, s18
	s_ashr_i32 s39, s38, 31
	s_lshl_b64 s[2:3], s[38:39], 19
	s_add_u32 s42, s16, s2
	s_addc_u32 s43, s17, s3
	s_and_b64 s[2:3], s[44:45], exec
	s_cselect_b32 s75, s43, s51
	s_cselect_b32 s76, s42, s50
	s_lshr_b32 s2, s69, 13
	v_lshl_add_u64 v[50:51], s[18:19], 0, v[136:137]
	v_lshl_add_u64 v[142:143], s[18:19], 0, v[138:139]
	s_and_b32 s26, s2, 0x40000
	v_lshl_add_u64 v[50:51], v[50:51], 0, s[24:25]
	v_lshl_add_u64 v[142:143], v[142:143], 0, s[24:25]
	s_mov_b32 s77, -2
	v_add_u32_e32 v246, 0x80, v132
	v_add_u32_e32 v247, 0x80, v134
